# static priority raise (s_setprio 1) for waves 4-7 for the whole attention queue loop, reset at the end (one wave per SIMD wins arbitration)
# baseline (speedup 1.0000x reference)
.LBB0_436:
	v_cvt_f32_u32_e32 v0, s37
	s_mov_b64 s[4:5], 0x2289000
	v_lshl_add_u64 v[156:157], v[102:103], 0, s[4:5]
	s_mov_b64 s[4:5], 0x2309000
	v_rcp_iflag_f32_e32 v0, v0
	v_lshl_add_u64 v[158:159], v[102:103], 0, s[4:5]
	s_mov_b64 s[4:5], 0x2b89000
	v_readlane_b32 s8, v255, 10
	v_lshl_add_u64 v[160:161], v[102:103], 0, s[4:5]
	s_mov_b64 s[4:5], 0x4b89000
	s_lshl_b32 s74, s8, 4
	v_mul_f32_e32 v0, 0x4f7ffffe, v0
	v_lshl_add_u64 v[162:163], v[102:103], 0, s[4:5]
	s_mov_b64 s[4:5], 0x6b89000
	v_lshl_add_u64 v[2:3], s[74:75], 2, v[102:103]
	s_mov_b32 s81, s75
	v_cvt_u32_f32_e32 v0, v0
	v_lshl_add_u64 v[164:165], v[102:103], 0, s[4:5]
	v_readlane_b32 s9, v255, 11
	v_lshl_add_u64 v[2:3], s[80:81], 2, v[2:3]
	s_mov_b64 s[4:5], 0x2188800
	v_lshl_add_u64 v[166:167], v[2:3], 0, s[4:5]
	s_lshl_b64 s[4:5], s[8:9], 5
	v_writelane_b32 v255, s4, 15
	s_lshl_b32 s40, s37, 8
	v_cmp_eq_u32_e64 s[34:35], 0, v194
	v_writelane_b32 v255, s5, 16
	s_sub_i32 s4, 0, s37
	v_readfirstlane_b32 s5, v0
	s_mul_i32 s4, s4, s5
	s_mul_hi_u32 s4, s5, s4
	s_add_i32 s41, s6, s40
	s_add_i32 s59, s5, s4
	s_add_i32 s81, s77, 0x4800
	s_add_i32 s44, s77, 0x4000
	s_cmp_lt_u32 s77, 0x12400
	s_cbranch_scc1 .Lattn_noprio
	s_setprio 1
.Lattn_noprio:
	s_branch .LBB0_440
.LBB0_437:
	v_and_b32_e32 v69, 3, v195
	v_or_b32_e32 v0, s58, v69
	v_lshlrev_b32_e32 v0, 7, v0
	v_lshl_add_u64 v[66:67], v[160:161], 0, v[0:1]
	v_lshl_add_u64 v[72:73], v[178:179], 0, s[74:75]
	v_lshlrev_b32_e32 v0, 1, v69
	v_lshl_add_u64 v[72:73], v[72:73], 0, v[0:1]
	v_add_co_u32_e32 v72, vcc, s90, v72
	v_mov_b32_e32 v71, v147
	s_nop 0
	v_addc_co_u32_e32 v73, vcc, 0, v73, vcc
	global_load_ushort v69, v[72:73], off offset:800
	v_mov_b32_e32 v70, v146
	v_permlane32_swap_b32_e32 v147, v71
	s_nop 0
	v_permlane32_swap_b32_e32 v146, v70
	v_pk_add_f32 v[70:71], v[146:147], v[70:71]
	v_lshl_add_u32 v68, v195, 2, s77
	v_rcp_f32_e32 v78, v71
	ds_read2st64_b32 v[74:75], v68 offset1:1
	ds_read2st64_b32 v[76:77], v68 offset0:2 offset1:3
	v_cmp_lt_f32_e64 s[4:5], 0, v71
	v_ashrrev_i32_e32 v151, 31, v150
	v_lshl_add_u64 v[66:67], v[150:151], 1, v[66:67]
	v_cndmask_b32_e64 v71, 0, v78, s[4:5]
	v_lshlrev_b64 v[72:73], 10, v[170:171]
	v_lshl_add_u64 v[72:73], v[66:67], 0, v[72:73]
	v_cmp_lt_f32_e32 vcc, 0, v70
	s_mov_b32 s82, 0x800000
	s_waitcnt vmcnt(0) lgkmcnt(0)
	v_lshlrev_b32_e32 v69, 16, v69
	v_mul_f32_e32 v78, v71, v69
	v_pk_fma_f32 v[50:51], v[50:51], v[78:79], v[74:75] op_sel_hi:[1,0,1]
	v_pk_fma_f32 v[52:53], v[52:53], v[78:79], v[76:77] op_sel_hi:[1,0,1]
	v_cvt_pk_bf16_f32 v50, v50, v51
	v_cvt_pk_bf16_f32 v51, v52, v53
	global_store_dwordx2 v[72:73], v[50:51], off
	ds_read2st64_b32 v[50:51], v68 offset0:4 offset1:5
	ds_read2st64_b32 v[52:53], v68 offset0:6 offset1:7
	s_waitcnt lgkmcnt(0)
	v_pk_fma_f32 v[50:51], v[54:55], v[78:79], v[50:51] op_sel_hi:[1,0,1]
	v_pk_fma_f32 v[52:53], v[56:57], v[78:79], v[52:53] op_sel_hi:[1,0,1]
	v_cvt_pk_bf16_f32 v50, v50, v51
	v_cvt_pk_bf16_f32 v51, v52, v53
	global_store_dwordx2 v[72:73], v[50:51], off offset:16
	ds_read2st64_b32 v[50:51], v68 offset0:8 offset1:9
	ds_read2st64_b32 v[52:53], v68 offset0:10 offset1:11
	s_waitcnt lgkmcnt(0)
	v_pk_fma_f32 v[50:51], v[58:59], v[78:79], v[50:51] op_sel_hi:[1,0,1]
	v_pk_fma_f32 v[52:53], v[60:61], v[78:79], v[52:53] op_sel_hi:[1,0,1]
	v_cvt_pk_bf16_f32 v50, v50, v51
	v_cvt_pk_bf16_f32 v51, v52, v53
	global_store_dwordx2 v[72:73], v[50:51], off offset:32
	ds_read2st64_b32 v[50:51], v68 offset0:12 offset1:13
	ds_read2st64_b32 v[52:53], v68 offset0:14 offset1:15
	s_waitcnt lgkmcnt(0)
	v_pk_fma_f32 v[50:51], v[62:63], v[78:79], v[50:51] op_sel_hi:[1,0,1]
	v_pk_fma_f32 v[52:53], v[64:65], v[78:79], v[52:53] op_sel_hi:[1,0,1]
	v_cvt_pk_bf16_f32 v50, v50, v51
	v_cvt_pk_bf16_f32 v51, v52, v53
	global_store_dwordx2 v[72:73], v[50:51], off offset:48
	ds_read2st64_b32 v[50:51], v68 offset0:16 offset1:17
	s_waitcnt lgkmcnt(0)
	v_pk_fma_f32 v[34:35], v[34:35], v[78:79], v[50:51] op_sel_hi:[1,0,1]
	ds_read2st64_b32 v[50:51], v68 offset0:18 offset1:19
	v_cvt_pk_bf16_f32 v34, v34, v35
	s_waitcnt lgkmcnt(0)
	v_pk_fma_f32 v[36:37], v[36:37], v[78:79], v[50:51] op_sel_hi:[1,0,1]
	s_nop 0
	v_cvt_pk_bf16_f32 v35, v36, v37
	global_store_dwordx2 v[72:73], v[34:35], off offset:64
	ds_read2st64_b32 v[34:35], v68 offset0:20 offset1:21
	ds_read2st64_b32 v[36:37], v68 offset0:22 offset1:23
	s_waitcnt lgkmcnt(0)
	v_pk_fma_f32 v[34:35], v[38:39], v[78:79], v[34:35] op_sel_hi:[1,0,1]
	v_pk_fma_f32 v[36:37], v[40:41], v[78:79], v[36:37] op_sel_hi:[1,0,1]
	v_cvt_pk_bf16_f32 v34, v34, v35
	v_cvt_pk_bf16_f32 v35, v36, v37
	global_store_dwordx2 v[72:73], v[34:35], off offset:80
	ds_read2st64_b32 v[34:35], v68 offset0:24 offset1:25
	ds_read2st64_b32 v[36:37], v68 offset0:26 offset1:27
	s_waitcnt lgkmcnt(0)
	v_pk_fma_f32 v[34:35], v[42:43], v[78:79], v[34:35] op_sel_hi:[1,0,1]
	v_pk_fma_f32 v[36:37], v[44:45], v[78:79], v[36:37] op_sel_hi:[1,0,1]
	v_cvt_pk_bf16_f32 v34, v34, v35
	v_cvt_pk_bf16_f32 v35, v36, v37
	global_store_dwordx2 v[72:73], v[34:35], off offset:96
	ds_read2st64_b32 v[34:35], v68 offset0:28 offset1:29
	ds_read2st64_b32 v[36:37], v68 offset0:30 offset1:31
	s_waitcnt lgkmcnt(0)
	v_pk_fma_f32 v[34:35], v[46:47], v[78:79], v[34:35] op_sel_hi:[1,0,1]
	v_pk_fma_f32 v[36:37], v[48:49], v[78:79], v[36:37] op_sel_hi:[1,0,1]
	v_cvt_pk_bf16_f32 v34, v34, v35
	v_cvt_pk_bf16_f32 v35, v36, v37
	global_store_dwordx2 v[72:73], v[34:35], off offset:112
	v_rcp_f32_e32 v34, v70
	s_nop 0
	v_cndmask_b32_e32 v36, 0, v34, vcc
	v_lshl_add_u64 v[34:35], v[176:177], 0, s[74:75]
	v_lshl_add_u64 v[34:35], v[34:35], 0, v[0:1]
	v_add_co_u32_e32 v34, vcc, s90, v34
	s_nop 1
	v_addc_co_u32_e32 v35, vcc, 0, v35, vcc
	global_load_ushort v0, v[34:35], off offset:800
	v_lshlrev_b64 v[34:35], 10, v[168:169]
	v_lshl_add_u64 v[34:35], v[66:67], 0, v[34:35]
	s_waitcnt vmcnt(0) lgkmcnt(0)
	v_lshlrev_b32_e32 v0, 16, v0
	v_mul_f32_e32 v0, v36, v0
	ds_read2st64_b32 v[36:37], v68 offset0:32 offset1:33
	s_waitcnt lgkmcnt(0)
	v_pk_fma_f32 v[18:19], v[18:19], v[0:1], v[36:37] op_sel_hi:[1,0,1]
	ds_read2st64_b32 v[36:37], v68 offset0:34 offset1:35
	v_cvt_pk_bf16_f32 v18, v18, v19
	s_waitcnt lgkmcnt(0)
	v_pk_fma_f32 v[20:21], v[20:21], v[0:1], v[36:37] op_sel_hi:[1,0,1]
	s_nop 0
	v_cvt_pk_bf16_f32 v19, v20, v21
	global_store_dwordx2 v[34:35], v[18:19], off
	ds_read2st64_b32 v[18:19], v68 offset0:36 offset1:37
	ds_read2st64_b32 v[20:21], v68 offset0:38 offset1:39
	s_waitcnt lgkmcnt(0)
	v_pk_fma_f32 v[18:19], v[22:23], v[0:1], v[18:19] op_sel_hi:[1,0,1]
	v_pk_fma_f32 v[20:21], v[24:25], v[0:1], v[20:21] op_sel_hi:[1,0,1]
	v_cvt_pk_bf16_f32 v18, v18, v19
	v_cvt_pk_bf16_f32 v19, v20, v21
	global_store_dwordx2 v[34:35], v[18:19], off offset:16
	ds_read2st64_b32 v[18:19], v68 offset0:40 offset1:41
	ds_read2st64_b32 v[20:21], v68 offset0:42 offset1:43
	s_waitcnt lgkmcnt(0)
	v_pk_fma_f32 v[18:19], v[26:27], v[0:1], v[18:19] op_sel_hi:[1,0,1]
	v_pk_fma_f32 v[20:21], v[28:29], v[0:1], v[20:21] op_sel_hi:[1,0,1]
	v_cvt_pk_bf16_f32 v18, v18, v19
	v_cvt_pk_bf16_f32 v19, v20, v21
	global_store_dwordx2 v[34:35], v[18:19], off offset:32
	ds_read2st64_b32 v[18:19], v68 offset0:44 offset1:45
	ds_read2st64_b32 v[20:21], v68 offset0:46 offset1:47
	s_waitcnt lgkmcnt(0)
	v_pk_fma_f32 v[18:19], v[30:31], v[0:1], v[18:19] op_sel_hi:[1,0,1]
	v_pk_fma_f32 v[20:21], v[32:33], v[0:1], v[20:21] op_sel_hi:[1,0,1]
	v_cvt_pk_bf16_f32 v18, v18, v19
	v_cvt_pk_bf16_f32 v19, v20, v21
	global_store_dwordx2 v[34:35], v[18:19], off offset:48
	ds_read2st64_b32 v[18:19], v68 offset0:48 offset1:49
	s_waitcnt lgkmcnt(0)
	v_pk_fma_f32 v[2:3], v[2:3], v[0:1], v[18:19] op_sel_hi:[1,0,1]
	ds_read2st64_b32 v[18:19], v68 offset0:50 offset1:51
	v_cvt_pk_bf16_f32 v2, v2, v3
	s_waitcnt lgkmcnt(0)
	v_pk_fma_f32 v[4:5], v[4:5], v[0:1], v[18:19] op_sel_hi:[1,0,1]
	s_nop 0
	v_cvt_pk_bf16_f32 v3, v4, v5
	global_store_dwordx2 v[34:35], v[2:3], off offset:64
	ds_read2st64_b32 v[2:3], v68 offset0:52 offset1:53
	ds_read2st64_b32 v[4:5], v68 offset0:54 offset1:55
	s_waitcnt lgkmcnt(0)
	v_pk_fma_f32 v[2:3], v[6:7], v[0:1], v[2:3] op_sel_hi:[1,0,1]
	v_pk_fma_f32 v[4:5], v[8:9], v[0:1], v[4:5] op_sel_hi:[1,0,1]
	v_cvt_pk_bf16_f32 v2, v2, v3
	v_cvt_pk_bf16_f32 v3, v4, v5
	global_store_dwordx2 v[34:35], v[2:3], off offset:80
	ds_read2st64_b32 v[2:3], v68 offset0:56 offset1:57
	ds_read2st64_b32 v[4:5], v68 offset0:58 offset1:59
	s_waitcnt lgkmcnt(0)
	v_pk_fma_f32 v[2:3], v[10:11], v[0:1], v[2:3] op_sel_hi:[1,0,1]
	v_pk_fma_f32 v[4:5], v[12:13], v[0:1], v[4:5] op_sel_hi:[1,0,1]
	v_cvt_pk_bf16_f32 v2, v2, v3
	v_cvt_pk_bf16_f32 v3, v4, v5
	global_store_dwordx2 v[34:35], v[2:3], off offset:96
	ds_read2st64_b32 v[2:3], v68 offset0:60 offset1:61
	ds_read2st64_b32 v[4:5], v68 offset0:62 offset1:63
	s_waitcnt lgkmcnt(0)
	v_pk_fma_f32 v[2:3], v[14:15], v[0:1], v[2:3] op_sel_hi:[1,0,1]
	v_pk_fma_f32 v[4:5], v[16:17], v[0:1], v[4:5] op_sel_hi:[1,0,1]
	v_cvt_pk_bf16_f32 v2, v2, v3
	v_cvt_pk_bf16_f32 v3, v4, v5
	global_store_dwordx2 v[34:35], v[2:3], off offset:112
	s_waitcnt lgkmcnt(0)

.LBB0_659:
	s_setprio 0
	v_readlane_b32 s56, v254, 60
	v_readlane_b32 s58, v254, 62
	v_readlane_b32 s76, v255, 0
	v_readlane_b32 s20, v255, 13
	v_readlane_b32 s57, v254, 61
	v_readlane_b32 s59, v254, 63
	v_readlane_b32 s77, v255, 1
	v_readlane_b32 s80, v255, 2
	v_readlane_b32 s81, v255, 3
	v_readlane_b32 s41, v255, 12
	v_readlane_b32 s21, v255, 14
